# diff-attention loop back-edge rotation: loop-control scalar ops moved into earlier slot gaps of the odd body, only the branch remains between the last and first MFMA
# baseline (speedup 1.0000x reference)
; #define ATT_LAS __attribute__((address_space(3)))
; #define SB0() __builtin_amdgcn_sched_barrier(0)
; __device__ __forceinline__ void hs_fast(f32x16& S, f32x16 (&O)[4], bf16x8 (&pf)[2], float& lsum, const bf16x8 (&qf)[4], const ATT_LAS unsigned char* ka, const ATT_LAS unsigned char* va) {
;     bf16x8 kf[4], vf[8]; f32x16 N; float acc;
;     const f32x16 Z = {0.f, 0.f, 0.f, 0.f, 0.f, 0.f, 0.f, 0.f, 0.f, 0.f, 0.f, 0.f, 0.f, 0.f, 0.f, 0.f};
;     kf[0] = LDF(ka); kf[1] = LDF(ka + 32); kf[2] = LDF(ka + 64); kf[3] = LDF(ka + 96);
;     vf[0] = LDF(va); vf[1] = LDF(va + 32 * VPITCH); vf[2] = LDF(va + 64 * VPITCH); vf[3] = LDF(va + 96 * VPITCH);
;     SB0();
;     N = MFMA32(kf[0], qf[0], Z);          S[0] = EX2(S[0]); S[1] = EX2(S[1]);
;     SB0();
;     O[0] = MFMA32(vf[0], pf[0], O[0]);    S[2] = EX2(S[2]); S[3] = EX2(S[3]); acc = S[0] + S[1];
;     SB0();
;     N = MFMA32(kf[1], qf[1], N);          S[4] = EX2(S[4]); S[5] = EX2(S[5]); acc += S[2]; acc += S[3];
;     SB0();
;     O[1] = MFMA32(vf[1], pf[0], O[1]);    S[6] = EX2(S[6]); S[7] = EX2(S[7]); acc += S[4]; acc += S[5];
;     SB0();
;     N = MFMA32(kf[2], qf[2], N);          S[8] = EX2(S[8]); S[9] = EX2(S[9]); acc += S[6]; acc += S[7];
;     vf[4] = LDF(va + 32); vf[5] = LDF(va + 32 * VPITCH + 32);
;     SB0();
;     O[2] = MFMA32(vf[2], pf[0], O[2]);    S[10] = EX2(S[10]); S[11] = EX2(S[11]); acc += S[8]; acc += S[9];
;     vf[6] = LDF(va + 64 * VPITCH + 32); vf[7] = LDF(va + 96 * VPITCH + 32);
;     SB0();
;     N = MFMA32(kf[3], qf[3], N);          S[12] = EX2(S[12]); S[13] = EX2(S[13]); acc += S[10]; acc += S[11];
;     SB0();
;     O[3] = MFMA32(vf[3], pf[0], O[3]);    S[14] = EX2(S[14]); S[15] = EX2(S[15]); acc += S[12]; acc += S[13];
;     SB0();
;     u32x4 w0, w1;
;     O[0] = MFMA32(vf[4], pf[1], O[0]);    w0.x = cvt_pk_bf16(S[0], S[1]); w0.y = cvt_pk_bf16(S[2], S[3]); acc += S[14]; acc += S[15];
;     SB0();
;     O[1] = MFMA32(vf[5], pf[1], O[1]);    w0.z = cvt_pk_bf16(S[4], S[5]); w0.w = cvt_pk_bf16(S[6], S[7]);
;     SB0();
;     O[2] = MFMA32(vf[6], pf[1], O[2]);    w1.x = cvt_pk_bf16(S[8], S[9]); w1.y = cvt_pk_bf16(S[10], S[11]);
;     SB0();
;     O[3] = MFMA32(vf[7], pf[1], O[3]);    w1.z = cvt_pk_bf16(S[12], S[13]); w1.w = cvt_pk_bf16(S[14], S[15]);
;     SB0();
;     lsum += acc; pf[0] = __builtin_bit_cast(bf16x8, w0); pf[1] = __builtin_bit_cast(bf16x8, w1); S = N;
; }
.Lfa_even:
	v_mov_b32_e32 v15, v1
	v_add_u32_e32 v1, s99, v196
	s_waitcnt lgkmcnt(9)
	v_mfma_f32_32x32x16_bf16 v[96:111], v[218:221], v[112:115], 0
	v_exp_f32_e32 v80, v80
	v_exp_f32_e32 v81, v81
	ds_read_b128 v[218:221], v14 offset:8800
	s_waitcnt lgkmcnt(8)
	v_add_f32_e32 v244, v80, v81
	v_mfma_f32_32x32x16_bf16 v[64:79], v[222:225], v[144:147], v[64:79]
	v_exp_f32_e32 v82, v82
	v_exp_f32_e32 v83, v83
	ds_read_b128 v[222:225], v15 offset:31296
	s_waitcnt lgkmcnt(7)
	v_add_f32_e32 v245, v82, v83
	v_mfma_f32_32x32x16_bf16 v[96:111], v[226:229], v[116:119], v[96:111]
	v_exp_f32_e32 v84, v84
	v_exp_f32_e32 v85, v85
	ds_read_b128 v[226:229], v15 offset:17504
	s_waitcnt lgkmcnt(6)
	v_add_f32_e32 v244, v244, v84
	v_add_f32_e32 v245, v245, v85
	v_mfma_f32_32x32x16_bf16 v[48:63], v[230:233], v[144:147], v[48:63]
	v_exp_f32_e32 v86, v86
	v_exp_f32_e32 v87, v87
	ds_read_b128 v[230:233], v15 offset:22112
	s_waitcnt lgkmcnt(5)
	v_add_f32_e32 v244, v244, v86
	v_add_f32_e32 v245, v245, v87
	v_mfma_f32_32x32x16_bf16 v[96:111], v[234:237], v[120:123], v[96:111]
	v_exp_f32_e32 v88, v88
	v_exp_f32_e32 v89, v89
	ds_read_b128 v[234:237], v15 offset:26720
	s_waitcnt lgkmcnt(5)
	v_add_f32_e32 v244, v244, v88
	v_add_f32_e32 v245, v245, v89
	v_mfma_f32_32x32x16_bf16 v[32:47], v[2:5], v[144:147], v[32:47]
	v_exp_f32_e32 v90, v90
	v_exp_f32_e32 v91, v91
	ds_read_b128 v[2:5], v15 offset:31328
	s_waitcnt lgkmcnt(5)
	v_add_f32_e32 v244, v244, v90
	v_add_f32_e32 v245, v245, v91
	v_mfma_f32_32x32x16_bf16 v[96:111], v[218:221], v[124:127], v[96:111]
	v_exp_f32_e32 v92, v92
	v_exp_f32_e32 v93, v93
	ds_read_b128 v[218:221], v1 offset:17408
	s_waitcnt lgkmcnt(5)
	v_add_f32_e32 v244, v244, v92
	v_add_f32_e32 v245, v245, v93
	v_mfma_f32_32x32x16_bf16 v[16:31], v[222:225], v[144:147], v[16:31]
	v_exp_f32_e32 v94, v94
	v_exp_f32_e32 v95, v95
	ds_read_b128 v[222:225], v1 offset:22016
	s_waitcnt lgkmcnt(5)
	v_add_f32_e32 v244, v244, v94
	v_add_f32_e32 v245, v245, v95
	v_mfma_f32_32x32x16_bf16 v[64:79], v[226:229], v[150:153], v[64:79]
	v_add_f32_e32 v161, v161, v244
	v_cvt_pk_bf16_f32 v6, v80, v81
	v_cvt_pk_bf16_f32 v7, v82, v83
	ds_read_b128 v[226:229], v1 offset:26624
	s_waitcnt lgkmcnt(5)
	v_mfma_f32_32x32x16_bf16 v[48:63], v[230:233], v[150:153], v[48:63]
	v_add_f32_e32 v161, v161, v245
	v_cvt_pk_bf16_f32 v8, v84, v85
	v_cvt_pk_bf16_f32 v9, v86, v87
	ds_read_b128 v[230:233], v1 offset:31232
	s_waitcnt lgkmcnt(5)
	v_mfma_f32_32x32x16_bf16 v[32:47], v[234:237], v[150:153], v[32:47]
	v_cvt_pk_bf16_f32 v10, v88, v89
	v_cvt_pk_bf16_f32 v11, v90, v91
	s_waitcnt lgkmcnt(4)
	v_mfma_f32_32x32x16_bf16 v[16:31], v[2:5], v[150:153], v[16:31]
	v_cvt_pk_bf16_f32 v12, v92, v93
	v_cvt_pk_bf16_f32 v13, v94, v95
	ds_read_b128 v[2:5], v1 offset:17440
	s_add_i32 s46, s46, 1
	s_cmp_eq_u32 s46, s24
	s_cbranch_scc1 .Lfa_exit_even
	s_cmp_eq_u32 s41, 0
	s_cbranch_scc0 .Lfa_odd_b
	s_barrier
	v_add_u32_e32 v14, s100, v163
	ds_read_b128 v[234:237], v14
	v_add_u32_e32 v246, s98, v193
	v_add_u32_e32 v247, s98, v194
	s_waitcnt lgkmcnt(5)
	v_mfma_f32_32x32x16_bf16 v[64:79], v[218:221], v[6:9], v[64:79]
	v_exp_f32_e32 v96, v96
	v_exp_f32_e32 v97, v97
	ds_read_b128 v[218:221], v14 offset:32
	s_waitcnt lgkmcnt(5)
	v_add_f32_e32 v244, v96, v97
	v_mfma_f32_32x32x16_bf16 v[48:63], v[222:225], v[6:9], v[48:63]
	v_exp_f32_e32 v98, v98
	v_exp_f32_e32 v99, v99
	ds_read_b128 v[222:225], v1 offset:22048
	s_waitcnt lgkmcnt(5)
	v_add_f32_e32 v245, v98, v99
	v_mfma_f32_32x32x16_bf16 v[32:47], v[226:229], v[6:9], v[32:47]
	v_exp_f32_e32 v100, v100
	v_exp_f32_e32 v101, v101
	ds_read_b128 v[226:229], v14 offset:64
	s_waitcnt lgkmcnt(5)
	v_add_f32_e32 v244, v244, v100
	v_add_f32_e32 v245, v245, v101
	v_mfma_f32_32x32x16_bf16 v[16:31], v[230:233], v[6:9], v[16:31]
	v_exp_f32_e32 v102, v102
	v_exp_f32_e32 v103, v103
	ds_read_b128 v[230:233], v1 offset:26656
	s_waitcnt lgkmcnt(4)
	v_add_f32_e32 v244, v244, v102
	v_add_f32_e32 v245, v245, v103
	v_mfma_f32_32x32x16_bf16 v[80:95], v[234:237], v[112:115], 0
	v_exp_f32_e32 v104, v104
	v_exp_f32_e32 v105, v105
	ds_read_b128 v[234:237], v14 offset:96
	s_waitcnt lgkmcnt(5)
	v_add_f32_e32 v244, v244, v104
	v_add_f32_e32 v245, v245, v105
	v_mfma_f32_32x32x16_bf16 v[64:79], v[2:5], v[10:13], v[64:79]
	v_exp_f32_e32 v106, v106
	v_exp_f32_e32 v107, v107
	ds_read_b128 v[2:5], v1 offset:31264
	s_waitcnt lgkmcnt(5)
	v_add_f32_e32 v244, v244, v106
	v_add_f32_e32 v245, v245, v107
	v_mfma_f32_32x32x16_bf16 v[80:95], v[218:221], v[116:119], v[80:95]
	v_exp_f32_e32 v108, v108
	v_exp_f32_e32 v109, v109
	ds_read_b128 v[218:221], v14 offset:8704
	v_add_f32_e32 v244, v244, v108
	v_add_f32_e32 v245, v245, v109
	s_waitcnt vmcnt(0)
	ds_write_b128 v246, v[128:131]
	s_mov_b32 s101, s98
	s_waitcnt lgkmcnt(6)
	v_mfma_f32_32x32x16_bf16 v[48:63], v[222:225], v[10:13], v[48:63]
	v_exp_f32_e32 v110, v110
	v_exp_f32_e32 v111, v111
	ds_read_b128 v[222:225], v1 offset:17472
	v_add_f32_e32 v244, v244, v110
	v_add_f32_e32 v245, v245, v111
	ds_write_b128 v247, v[132:135] offset:17408
	s_mov_b32 s98, s99
	s_waitcnt lgkmcnt(7)
	v_mfma_f32_32x32x16_bf16 v[80:95], v[226:229], v[120:123], v[80:95]
	v_add_f32_e32 v161, v161, v244
	v_cvt_pk_bf16_f32 v144, v96, v97
	v_cvt_pk_bf16_f32 v145, v98, v99
	ds_read_b128 v[226:229], v14 offset:8736
	ds_write_b128 v246, v[136:139] offset:8704
	s_mov_b32 s99, s100
	s_waitcnt lgkmcnt(8)
	v_mfma_f32_32x32x16_bf16 v[32:47], v[230:233], v[10:13], v[32:47]
	v_add_f32_e32 v161, v161, v245
	v_cvt_pk_bf16_f32 v146, v100, v101
	v_cvt_pk_bf16_f32 v147, v102, v103
	ds_read_b128 v[230:233], v1 offset:22080
	ds_write_b128 v247, v[140:143] offset:26624
	s_mov_b32 s100, s101
	s_waitcnt lgkmcnt(9)
	v_mfma_f32_32x32x16_bf16 v[80:95], v[234:237], v[124:127], v[80:95]
	v_cvt_pk_bf16_f32 v150, v104, v105
	v_cvt_pk_bf16_f32 v151, v106, v107
	ds_read_b128 v[234:237], v14 offset:8768
	s_cmp_ge_u32 s47, s23
	s_cbranch_scc1 .Lfa_noload
	s_lshl_b32 s48, s47, 17
	s_lshl_b32 s4, s47, 7
	s_add_u32 s48, s20, s48
	s_addc_u32 s49, s21, 0
	global_load_dwordx4 v[128:131], v240, s[48:49]
	s_add_u32 s4, s12, s4
	s_addc_u32 s25, s13, 0
	s_mov_b32 s5, s25
	global_load_dwordx4 v[132:135], v242, s[4:5]
	global_load_dwordx4 v[136:139], v241, s[48:49]
	global_load_dwordx4 v[140:143], v243, s[4:5]
	s_mov_b32 s5, 0
; #define ATT_LAS __attribute__((address_space(3)))
; #define SB0() __builtin_amdgcn_sched_barrier(0)
; __device__ __forceinline__ void hs_fast(f32x16& S, f32x16 (&O)[4], bf16x8 (&pf)[2], float& lsum, const bf16x8 (&qf)[4], const ATT_LAS unsigned char* ka, const ATT_LAS unsigned char* va) {
;     bf16x8 kf[4], vf[8]; f32x16 N; float acc;
;     const f32x16 Z = {0.f, 0.f, 0.f, 0.f, 0.f, 0.f, 0.f, 0.f, 0.f, 0.f, 0.f, 0.f, 0.f, 0.f, 0.f, 0.f};
;     kf[0] = LDF(ka); kf[1] = LDF(ka + 32); kf[2] = LDF(ka + 64); kf[3] = LDF(ka + 96);
;     vf[0] = LDF(va); vf[1] = LDF(va + 32 * VPITCH); vf[2] = LDF(va + 64 * VPITCH); vf[3] = LDF(va + 96 * VPITCH);
;     SB0();
;     N = MFMA32(kf[0], qf[0], Z);          S[0] = EX2(S[0]); S[1] = EX2(S[1]);
;     SB0();
;     O[0] = MFMA32(vf[0], pf[0], O[0]);    S[2] = EX2(S[2]); S[3] = EX2(S[3]); acc = S[0] + S[1];
;     SB0();
;     N = MFMA32(kf[1], qf[1], N);          S[4] = EX2(S[4]); S[5] = EX2(S[5]); acc += S[2]; acc += S[3];
;     SB0();
;     O[1] = MFMA32(vf[1], pf[0], O[1]);    S[6] = EX2(S[6]); S[7] = EX2(S[7]); acc += S[4]; acc += S[5];
;     SB0();
;     N = MFMA32(kf[2], qf[2], N);          S[8] = EX2(S[8]); S[9] = EX2(S[9]); acc += S[6]; acc += S[7];
;     vf[4] = LDF(va + 32); vf[5] = LDF(va + 32 * VPITCH + 32);
;     SB0();
;     O[2] = MFMA32(vf[2], pf[0], O[2]);    S[10] = EX2(S[10]); S[11] = EX2(S[11]); acc += S[8]; acc += S[9];
;     vf[6] = LDF(va + 64 * VPITCH + 32); vf[7] = LDF(va + 96 * VPITCH + 32);
;     SB0();
;     N = MFMA32(kf[3], qf[3], N);          S[12] = EX2(S[12]); S[13] = EX2(S[13]); acc += S[10]; acc += S[11];
;     SB0();
;     O[3] = MFMA32(vf[3], pf[0], O[3]);    S[14] = EX2(S[14]); S[15] = EX2(S[15]); acc += S[12]; acc += S[13];
;     SB0();
;     u32x4 w0, w1;
;     O[0] = MFMA32(vf[4], pf[1], O[0]);    w0.x = cvt_pk_bf16(S[0], S[1]); w0.y = cvt_pk_bf16(S[2], S[3]); acc += S[14]; acc += S[15];
;     SB0();
;     O[1] = MFMA32(vf[5], pf[1], O[1]);    w0.z = cvt_pk_bf16(S[4], S[5]); w0.w = cvt_pk_bf16(S[6], S[7]);
;     SB0();
;     O[2] = MFMA32(vf[6], pf[1], O[2]);    w1.x = cvt_pk_bf16(S[8], S[9]); w1.y = cvt_pk_bf16(S[10], S[11]);
;     SB0();
;     O[3] = MFMA32(vf[7], pf[1], O[3]);    w1.z = cvt_pk_bf16(S[12], S[13]); w1.w = cvt_pk_bf16(S[14], S[15]);
;     SB0();
;     lsum += acc; pf[0] = __builtin_bit_cast(bf16x8, w0); pf[1] = __builtin_bit_cast(bf16x8, w1); S = N;
; }
.Lfa_noload:
	s_add_i32 s47, s47, 1
	s_add_i32 s46, s46, 1
	s_cmp_eq_u32 s46, s24
	s_waitcnt lgkmcnt(9)
	v_mfma_f32_32x32x16_bf16 v[16:31], v[2:5], v[10:13], v[16:31]
	v_cvt_pk_bf16_f32 v152, v108, v109
	v_cvt_pk_bf16_f32 v153, v110, v111
	ds_read_b128 v[2:5], v1 offset:26688
	s_branch .Lfa_odd_join
.Lfa_odd_b:
	s_waitcnt lgkmcnt(4)
	v_mfma_f32_32x32x16_bf16 v[64:79], v[218:221], v[6:9], v[64:79]
	v_exp_f32_e32 v96, v96
	v_exp_f32_e32 v97, v97
	ds_read_b128 v[218:221], v1 offset:22048
	s_waitcnt lgkmcnt(4)
	v_add_f32_e32 v244, v96, v97
	v_mfma_f32_32x32x16_bf16 v[48:63], v[222:225], v[6:9], v[48:63]
	v_exp_f32_e32 v98, v98
	v_exp_f32_e32 v99, v99
	ds_read_b128 v[222:225], v1 offset:26656
	s_waitcnt lgkmcnt(4)
	v_add_f32_e32 v245, v98, v99
	v_mfma_f32_32x32x16_bf16 v[32:47], v[226:229], v[6:9], v[32:47]
	v_exp_f32_e32 v100, v100
	v_exp_f32_e32 v101, v101
	ds_read_b128 v[226:229], v1 offset:31264
	s_waitcnt lgkmcnt(4)
	v_add_f32_e32 v244, v244, v100
	v_add_f32_e32 v245, v245, v101
	v_mfma_f32_32x32x16_bf16 v[16:31], v[230:233], v[6:9], v[16:31]
	v_exp_f32_e32 v102, v102
	v_exp_f32_e32 v103, v103
	v_add_f32_e32 v244, v244, v102
	v_add_f32_e32 v245, v245, v103
	s_waitcnt lgkmcnt(3)
	v_mfma_f32_32x32x16_bf16 v[64:79], v[2:5], v[10:13], v[64:79]
	v_exp_f32_e32 v104, v104
	v_exp_f32_e32 v105, v105
	v_add_f32_e32 v244, v244, v104
	v_add_f32_e32 v245, v245, v105
	s_barrier
	v_add_u32_e32 v14, s100, v163
	ds_read_b128 v[230:233], v14
	ds_read_b128 v[234:237], v14 offset:32
	ds_read_b128 v[2:5], v14 offset:64
	ds_read_b128 v[248:251], v14 offset:96
	v_add_u32_e32 v246, s98, v193
	v_add_u32_e32 v247, s98, v194
	s_waitcnt lgkmcnt(6)
	v_mfma_f32_32x32x16_bf16 v[48:63], v[218:221], v[10:13], v[48:63]
	v_exp_f32_e32 v106, v106
	v_exp_f32_e32 v107, v107
	ds_read_b128 v[218:221], v14 offset:8704
	s_waitcnt lgkmcnt(6)
	v_add_f32_e32 v244, v244, v106
	v_add_f32_e32 v245, v245, v107
	v_mfma_f32_32x32x16_bf16 v[32:47], v[222:225], v[10:13], v[32:47]
	v_exp_f32_e32 v108, v108
	v_exp_f32_e32 v109, v109
	ds_read_b128 v[222:225], v1 offset:17472
	s_waitcnt lgkmcnt(6)
	v_add_f32_e32 v244, v244, v108
	v_add_f32_e32 v245, v245, v109
	v_mfma_f32_32x32x16_bf16 v[16:31], v[226:229], v[10:13], v[16:31]
	v_exp_f32_e32 v110, v110
	v_exp_f32_e32 v111, v111
	ds_read_b128 v[226:229], v14 offset:8736
	v_add_f32_e32 v244, v244, v110
	v_add_f32_e32 v245, v245, v111
	s_waitcnt vmcnt(0)
	ds_write_b128 v246, v[128:131]
	s_mov_b32 s101, s98
	s_waitcnt lgkmcnt(7)
	v_mfma_f32_32x32x16_bf16 v[80:95], v[230:233], v[112:115], 0
	v_add_f32_e32 v161, v161, v244
	v_cvt_pk_bf16_f32 v144, v96, v97
	v_cvt_pk_bf16_f32 v145, v98, v99
	ds_read_b128 v[230:233], v1 offset:22080
	ds_write_b128 v247, v[132:135] offset:17408
	s_mov_b32 s98, s99
	s_waitcnt lgkmcnt(8)
	v_mfma_f32_32x32x16_bf16 v[80:95], v[234:237], v[116:119], v[80:95]
	v_add_f32_e32 v161, v161, v245
	v_cvt_pk_bf16_f32 v146, v100, v101
	v_cvt_pk_bf16_f32 v147, v102, v103
	ds_read_b128 v[234:237], v14 offset:8768
	ds_write_b128 v246, v[136:139] offset:8704
	s_mov_b32 s99, s100
	s_waitcnt lgkmcnt(9)
	v_mfma_f32_32x32x16_bf16 v[80:95], v[2:5], v[120:123], v[80:95]
	v_cvt_pk_bf16_f32 v150, v104, v105
	v_cvt_pk_bf16_f32 v151, v106, v107
	ds_read_b128 v[2:5], v1 offset:26688
	ds_write_b128 v247, v[140:143] offset:26624
	s_mov_b32 s100, s101
	s_waitcnt lgkmcnt(10)
	v_mfma_f32_32x32x16_bf16 v[80:95], v[248:251], v[124:127], v[80:95]
	v_cvt_pk_bf16_f32 v152, v108, v109
	v_cvt_pk_bf16_f32 v153, v110, v111
	s_cmp_ge_u32 s47, s23
	s_cbranch_scc1 .Lfa_noload_b
	s_lshl_b32 s48, s47, 17
	s_lshl_b32 s4, s47, 7
	s_add_u32 s48, s20, s48
	s_addc_u32 s49, s21, 0
	global_load_dwordx4 v[128:131], v240, s[48:49]
	s_add_u32 s4, s12, s4
	s_addc_u32 s25, s13, 0
	s_mov_b32 s5, s25
	global_load_dwordx4 v[132:135], v242, s[4:5]
	global_load_dwordx4 v[136:139], v241, s[48:49]
	global_load_dwordx4 v[140:143], v243, s[4:5]
	s_mov_b32 s5, 0
.Lfa_noload_b:
	s_add_i32 s47, s47, 1
	s_add_i32 s46, s46, 1
	s_cmp_eq_u32 s46, s24
.Lfa_odd_join:
	s_cbranch_scc0 .Lfa_even
	s_waitcnt lgkmcnt(0)
	v_mov_b32_e32 v148, v150
	v_mov_b32_e32 v149, v151
	s_mov_b32 s4, s42
	s_lshl_b32 s24, s23, 1
	s_cmp_gt_u32 s4, s24
	s_cbranch_scc1 .LBB0_556
	s_branch .LBB0_544
